# final output stores nt (streaming) on top of previous best
# baseline (speedup 1.0000x reference)
;     __device__ __forceinline__ void fused(f32x4 (&acc)[2][2][4][2], const Unit& u, int wr, int wc, int fr, int fq, PG8_LAS unsigned char* lds, int wid, int lane) const {
;     ...
;         asm volatile("s_waitcnt lgkmcnt(0)" ::: "memory"); __builtin_amdgcn_s_barrier(); asm volatile("" ::: "memory");
;         const bool bad = false;
;         f32x4 gv[2][2];
; #pragma unroll
;         for (int bj = 0; bj < 2; ++bj)
; #pragma unroll
;             for (int n = 0; n < 2; ++n) gv[bj][n] = *(const f32x4*)(gfin + col0 + bj * HALF + n * 16);
;         const float qnan = __builtin_nanf("");
; #pragma unroll
;         for (int ai = 0; ai < 2; ++ai)
; #pragma unroll
;             for (int m = 0; m < 4; ++m) { const int r = ai * HALF + wr * 64 + m * 16 + fr; const float sr = bad ? qnan : S[r]; const size_t off = (size_t)(u.pm * BM + r) * 2048 + col0;
; #pragma unroll
;                 for (int bj = 0; bj < 2; ++bj)
; #pragma unroll
;                     for (int n = 0; n < 2; ++n) { const f32x4 a_ = acc[ai][bj][m][n], g_ = gv[bj][n]; const f32x2 sp_ = {sr, sr}, al_ = {a_[0], a_[1]}, ah_ = {a_[2], a_[3]}, gl_ = {g_[0], g_[1]}, gh_ = {g_[2], g_[3]};
;                         const f32x2 yl_ = (al_ * sp_) * gl_, yh_ = (ah_ * sp_) * gh_;
;                         *(f32x4*)(out + off + bj * HALF + n * 16) = (f32x4){yl_[0], yl_[1], yh_[0], yh_[1]}; } }
.LBB0_1065:
	s_or_b64 exec, exec, s[2:3]
	s_waitcnt lgkmcnt(0)
	s_barrier
	v_lshlrev_b32_e32 v160, 2, v160
	global_load_dwordx4 v[12:15], v160, s[66:67]
	global_load_dwordx4 v[8:11], v160, s[66:67] offset:64
	global_load_dwordx4 v[4:7], v160, s[66:67] offset:512
	global_load_dwordx4 v[0:3], v160, s[66:67] offset:576
	v_lshl_add_u32 v162, v162, 2, 0
	v_add_u32_e32 v186, 0x1000, v162
	ds_read2_b32 v[162:163], v186 offset1:16
	ds_read2_b32 v[166:167], v186 offset0:32 offset1:48
	v_lshlrev_b64 v[130:131], 13, v[130:131]
	v_mov_b32_e32 v161, 0
	v_lshl_add_u64 v[130:131], s[68:69], 0, v[130:131]
	v_lshlrev_b64 v[132:133], 13, v[132:133]
	v_lshlrev_b64 v[134:135], 13, v[134:135]
	v_lshl_add_u64 v[164:165], v[130:131], 0, v[160:161]
	s_waitcnt lgkmcnt(1)
	v_pk_mul_f32 v[126:127], v[126:127], v[162:163] op_sel_hi:[1,0]
	v_pk_mul_f32 v[128:129], v[128:129], v[162:163] op_sel_hi:[1,0]
	v_mov_b32_e32 v130, v163
	v_lshl_add_u64 v[132:133], s[68:69], 0, v[132:133]
	v_lshl_add_u64 v[134:135], s[68:69], 0, v[134:135]
	v_pk_mul_f32 v[122:123], v[122:123], v[162:163] op_sel_hi:[1,0]
	v_pk_mul_f32 v[124:125], v[124:125], v[162:163] op_sel_hi:[1,0]
	v_pk_mul_f32 v[118:119], v[118:119], v[162:163] op_sel_hi:[1,0]
	v_pk_mul_f32 v[120:121], v[120:121], v[162:163] op_sel_hi:[1,0]
	v_pk_mul_f32 v[114:115], v[114:115], v[162:163] op_sel_hi:[1,0]
	v_pk_mul_f32 v[116:117], v[116:117], v[162:163] op_sel_hi:[1,0]
	s_waitcnt lgkmcnt(0)
	v_pk_mul_f32 v[136:137], v[136:137], v[166:167] op_sel_hi:[1,0]
	v_pk_mul_f32 v[162:163], v[96:97], v[166:167] op_sel_hi:[1,0]
	v_pk_mul_f32 v[168:169], v[94:95], v[166:167] op_sel_hi:[1,0]
	v_pk_mul_f32 v[170:171], v[92:93], v[166:167] op_sel_hi:[1,0]
	v_pk_mul_f32 v[172:173], v[90:91], v[166:167] op_sel_hi:[1,0]
	v_pk_mul_f32 v[174:175], v[88:89], v[166:167] op_sel_hi:[1,0]
	v_pk_mul_f32 v[176:177], v[86:87], v[166:167] op_sel_hi:[1,0]
	v_pk_mul_f32 v[178:179], v[84:85], v[166:167] op_sel_hi:[1,0]
	v_pk_mul_f32 v[110:111], v[110:111], v[130:131] op_sel_hi:[1,0]
	v_pk_mul_f32 v[112:113], v[112:113], v[130:131] op_sel_hi:[1,0]
	v_pk_mul_f32 v[180:181], v[106:107], v[130:131] op_sel_hi:[1,0]
	v_pk_mul_f32 v[106:107], v[108:109], v[130:131] op_sel_hi:[1,0]
	v_pk_mul_f32 v[108:109], v[102:103], v[130:131] op_sel_hi:[1,0]
	v_pk_mul_f32 v[182:183], v[104:105], v[130:131] op_sel_hi:[1,0]
	v_pk_mul_f32 v[184:185], v[98:99], v[130:131] op_sel_hi:[1,0]
	v_pk_mul_f32 v[130:131], v[100:101], v[130:131] op_sel_hi:[1,0]
	v_lshl_add_u64 v[132:133], v[132:133], 0, v[160:161]
	v_lshl_add_u64 v[134:135], v[134:135], 0, v[160:161]
	v_lshlrev_b64 v[82:83], 13, v[82:83]
	v_lshl_add_u64 v[82:83], s[68:69], 0, v[82:83]
	v_lshl_add_u64 v[82:83], v[82:83], 0, v[160:161]
	s_waitcnt vmcnt(3)
	v_pk_mul_f32 v[86:87], v[14:15], v[128:129]
	v_pk_mul_f32 v[84:85], v[12:13], v[126:127]
	s_waitcnt vmcnt(2)
	v_pk_mul_f32 v[90:91], v[10:11], v[124:125]
	v_pk_mul_f32 v[88:89], v[8:9], v[122:123]
	s_waitcnt vmcnt(1)
	v_pk_mul_f32 v[94:95], v[6:7], v[120:121]
	v_pk_mul_f32 v[92:93], v[4:5], v[118:119]
	s_waitcnt vmcnt(0)
	v_pk_mul_f32 v[98:99], v[2:3], v[116:117]
	v_pk_mul_f32 v[96:97], v[0:1], v[114:115]
	v_pk_mul_f32 v[102:103], v[14:15], v[112:113]
	v_pk_mul_f32 v[100:101], v[12:13], v[110:111]
	v_pk_mul_f32 v[106:107], v[10:11], v[106:107]
	v_pk_mul_f32 v[104:105], v[8:9], v[180:181]
	v_pk_mul_f32 v[110:111], v[6:7], v[182:183]
	v_pk_mul_f32 v[108:109], v[4:5], v[108:109]
	v_pk_mul_f32 v[114:115], v[2:3], v[130:131]
	v_pk_mul_f32 v[112:113], v[0:1], v[184:185]
	v_pk_mul_f32 v[118:119], v[14:15], v[162:163]
	v_pk_mul_f32 v[116:117], v[12:13], v[136:137]
	v_pk_mul_f32 v[122:123], v[10:11], v[170:171]
	v_pk_mul_f32 v[120:121], v[8:9], v[168:169]
	v_pk_mul_f32 v[126:127], v[6:7], v[174:175]
	v_pk_mul_f32 v[124:125], v[4:5], v[172:173]
	v_pk_mul_f32 v[130:131], v[2:3], v[178:179]
	v_pk_mul_f32 v[128:129], v[0:1], v[176:177]
	global_store_dwordx4 v[164:165], v[84:87], off nt
	global_store_dwordx4 v[164:165], v[88:91], off offset:64 nt
	global_store_dwordx4 v[164:165], v[92:95], off offset:512 nt
	global_store_dwordx4 v[164:165], v[96:99], off offset:576 nt
	global_store_dwordx4 v[132:133], v[100:103], off nt
	global_store_dwordx4 v[132:133], v[104:107], off offset:64 nt
	global_store_dwordx4 v[132:133], v[108:111], off offset:512 nt
	global_store_dwordx4 v[132:133], v[112:115], off offset:576 nt
	global_store_dwordx4 v[134:135], v[116:119], off nt
	global_store_dwordx4 v[134:135], v[120:123], off offset:64 nt
	global_store_dwordx4 v[134:135], v[124:127], off offset:512 nt
	global_store_dwordx4 v[134:135], v[128:131], off offset:576 nt
	v_mov_b32_e32 v84, v167
	v_pk_mul_f32 v[70:71], v[70:71], v[84:85] op_sel_hi:[1,0]
	v_pk_mul_f32 v[72:73], v[72:73], v[84:85] op_sel_hi:[1,0]
	v_pk_mul_f32 v[70:71], v[4:5], v[70:71]
	v_pk_mul_f32 v[72:73], v[6:7], v[72:73]
	global_store_dwordx4 v[82:83], v[70:73], off offset:512 nt
	ds_read2_b32 v[70:71], v186 offset0:128 offset1:144
	v_pk_mul_f32 v[66:67], v[66:67], v[84:85] op_sel_hi:[1,0]
	v_pk_mul_f32 v[68:69], v[68:69], v[84:85] op_sel_hi:[1,0]
	v_pk_mul_f32 v[66:67], v[0:1], v[66:67]
	v_pk_mul_f32 v[68:69], v[2:3], v[68:69]
	global_store_dwordx4 v[82:83], v[66:69], off offset:576 nt
	s_waitcnt lgkmcnt(0)
;     __device__ __forceinline__ void fused(f32x4 (&acc)[2][2][4][2], const Unit& u, int wr, int wc, int fr, int fq, PG8_LAS unsigned char* lds, int wid, int lane) const {
;     ...
;         const float qnan = __builtin_nanf("");
; #pragma unroll
;         for (int ai = 0; ai < 2; ++ai)
; #pragma unroll
;             for (int m = 0; m < 4; ++m) { const int r = ai * HALF + wr * 64 + m * 16 + fr; const float sr = bad ? qnan : S[r]; const size_t off = (size_t)(u.pm * BM + r) * 2048 + col0;
; #pragma unroll
;                 for (int bj = 0; bj < 2; ++bj)
; #pragma unroll
;                     for (int n = 0; n < 2; ++n) { const f32x4 a_ = acc[ai][bj][m][n], g_ = gv[bj][n]; const f32x2 sp_ = {sr, sr}, al_ = {a_[0], a_[1]}, ah_ = {a_[2], a_[3]}, gl_ = {g_[0], g_[1]}, gh_ = {g_[2], g_[3]};
;                         const f32x2 yl_ = (al_ * sp_) * gl_, yh_ = (ah_ * sp_) * gh_;
;                         *(f32x4*)(out + off + bj * HALF + n * 16) = (f32x4){yl_[0], yl_[1], yh_[0], yh_[1]}; } }
	v_pk_mul_f32 v[50:51], v[50:51], v[70:71] op_sel_hi:[1,0]
	v_pk_mul_f32 v[52:53], v[52:53], v[70:71] op_sel_hi:[1,0]
	v_lshlrev_b64 v[66:67], 13, v[138:139]
	v_lshl_add_u64 v[66:67], s[68:69], 0, v[66:67]
	v_lshl_add_u64 v[66:67], v[66:67], 0, v[160:161]
	v_pk_mul_f32 v[52:53], v[2:3], v[52:53]
	v_pk_mul_f32 v[50:51], v[0:1], v[50:51]
	global_store_dwordx4 v[66:67], v[50:53], off offset:576 nt
	v_pk_mul_f32 v[78:79], v[78:79], v[84:85] op_sel_hi:[1,0]
	v_pk_mul_f32 v[80:81], v[80:81], v[84:85] op_sel_hi:[1,0]
	v_lshlrev_b64 v[50:51], 13, v[142:143]
	v_mov_b32_e32 v52, v71
	v_lshl_add_u64 v[50:51], s[68:69], 0, v[50:51]
	v_pk_mul_f32 v[38:39], v[38:39], v[52:53] op_sel_hi:[1,0]
	v_pk_mul_f32 v[40:41], v[40:41], v[52:53] op_sel_hi:[1,0]
	v_lshl_add_u64 v[50:51], v[50:51], 0, v[160:161]
	v_pk_mul_f32 v[40:41], v[6:7], v[40:41]
	v_pk_mul_f32 v[38:39], v[4:5], v[38:39]
	global_store_dwordx4 v[50:51], v[38:41], off offset:512 nt
	ds_read2_b32 v[38:39], v186 offset0:160 offset1:176
	v_pk_mul_f32 v[34:35], v[34:35], v[52:53] op_sel_hi:[1,0]
	v_pk_mul_f32 v[36:37], v[36:37], v[52:53] op_sel_hi:[1,0]
	v_pk_mul_f32 v[34:35], v[0:1], v[34:35]
	v_pk_mul_f32 v[36:37], v[2:3], v[36:37]
	global_store_dwordx4 v[50:51], v[34:37], off offset:576 nt
	s_waitcnt lgkmcnt(0)
	v_pk_mul_f32 v[18:19], v[18:19], v[38:39] op_sel_hi:[1,0]
	v_pk_mul_f32 v[20:21], v[20:21], v[38:39] op_sel_hi:[1,0]
	v_lshlrev_b64 v[34:35], 13, v[144:145]
	v_lshl_add_u64 v[34:35], s[68:69], 0, v[34:35]
	v_lshl_add_u64 v[34:35], v[34:35], 0, v[160:161]
	v_pk_mul_f32 v[22:23], v[22:23], v[38:39] op_sel_hi:[1,0]
	v_pk_mul_f32 v[24:25], v[24:25], v[38:39] op_sel_hi:[1,0]
	v_pk_mul_f32 v[20:21], v[2:3], v[20:21]
	v_pk_mul_f32 v[18:19], v[0:1], v[18:19]
	v_pk_mul_f32 v[24:25], v[6:7], v[24:25]
	v_pk_mul_f32 v[22:23], v[4:5], v[22:23]
	global_store_dwordx4 v[34:35], v[18:21], off offset:576 nt
	v_pk_mul_f32 v[62:63], v[62:63], v[70:71] op_sel_hi:[1,0]
	v_pk_mul_f32 v[64:65], v[64:65], v[70:71] op_sel_hi:[1,0]
	v_lshlrev_b64 v[18:19], 13, v[146:147]
	v_mov_b32_e32 v20, v39
	v_pk_mul_f32 v[46:47], v[46:47], v[52:53] op_sel_hi:[1,0]
	v_pk_mul_f32 v[48:49], v[48:49], v[52:53] op_sel_hi:[1,0]
	v_pk_mul_f32 v[30:31], v[30:31], v[38:39] op_sel_hi:[1,0]
	v_pk_mul_f32 v[32:33], v[32:33], v[38:39] op_sel_hi:[1,0]
	global_store_dwordx4 v[34:35], v[22:25], off offset:512 nt
	v_lshl_add_u64 v[18:19], s[68:69], 0, v[18:19]
	v_pk_mul_f32 v[80:81], v[14:15], v[80:81]
	v_pk_mul_f32 v[22:23], v[158:159], v[20:21] op_sel_hi:[1,0]
	v_pk_mul_f32 v[24:25], v[156:157], v[20:21] op_sel_hi:[1,0]
	v_pk_mul_f32 v[78:79], v[12:13], v[78:79]
	v_pk_mul_f32 v[64:65], v[14:15], v[64:65]
	v_pk_mul_f32 v[62:63], v[12:13], v[62:63]
	v_pk_mul_f32 v[48:49], v[14:15], v[48:49]
	v_pk_mul_f32 v[46:47], v[12:13], v[46:47]
	v_pk_mul_f32 v[32:33], v[14:15], v[32:33]
	v_pk_mul_f32 v[30:31], v[12:13], v[30:31]
	v_pk_mul_f32 v[14:15], v[14:15], v[24:25]
	v_pk_mul_f32 v[12:13], v[12:13], v[22:23]
	v_lshl_add_u64 v[18:19], v[18:19], 0, v[160:161]
	global_store_dwordx4 v[82:83], v[78:81], off nt
	v_pk_mul_f32 v[74:75], v[74:75], v[84:85] op_sel_hi:[1,0]
	v_pk_mul_f32 v[76:77], v[76:77], v[84:85] op_sel_hi:[1,0]
	v_pk_mul_f32 v[58:59], v[58:59], v[70:71] op_sel_hi:[1,0]
	v_pk_mul_f32 v[60:61], v[60:61], v[70:71] op_sel_hi:[1,0]
	v_pk_mul_f32 v[42:43], v[42:43], v[52:53] op_sel_hi:[1,0]
	v_pk_mul_f32 v[44:45], v[44:45], v[52:53] op_sel_hi:[1,0]
	v_pk_mul_f32 v[26:27], v[26:27], v[38:39] op_sel_hi:[1,0]
	v_pk_mul_f32 v[28:29], v[28:29], v[38:39] op_sel_hi:[1,0]
	global_store_dwordx4 v[18:19], v[12:15], off nt
	v_pk_mul_f32 v[76:77], v[10:11], v[76:77]
	v_pk_mul_f32 v[74:75], v[8:9], v[74:75]
	v_pk_mul_f32 v[12:13], v[154:155], v[20:21] op_sel_hi:[1,0]
	v_pk_mul_f32 v[14:15], v[152:153], v[20:21] op_sel_hi:[1,0]
	v_pk_mul_f32 v[60:61], v[10:11], v[60:61]
	v_pk_mul_f32 v[58:59], v[8:9], v[58:59]
	v_pk_mul_f32 v[44:45], v[10:11], v[44:45]
	v_pk_mul_f32 v[42:43], v[8:9], v[42:43]
	v_pk_mul_f32 v[28:29], v[10:11], v[28:29]
	v_pk_mul_f32 v[26:27], v[8:9], v[26:27]
	v_pk_mul_f32 v[10:11], v[10:11], v[14:15]
	v_pk_mul_f32 v[8:9], v[8:9], v[12:13]
	global_store_dwordx4 v[82:83], v[74:77], off offset:64 nt
	v_pk_mul_f32 v[54:55], v[54:55], v[70:71] op_sel_hi:[1,0]
	v_pk_mul_f32 v[56:57], v[56:57], v[70:71] op_sel_hi:[1,0]
	global_store_dwordx4 v[18:19], v[8:11], off offset:64 nt
	v_pk_mul_f32 v[56:57], v[6:7], v[56:57]
	v_pk_mul_f32 v[54:55], v[4:5], v[54:55]
	v_pk_mul_f32 v[8:9], v[150:151], v[20:21] op_sel_hi:[1,0]
	v_pk_mul_f32 v[10:11], v[140:141], v[20:21] op_sel_hi:[1,0]
	v_pk_mul_f32 v[4:5], v[4:5], v[8:9]
	v_pk_mul_f32 v[6:7], v[6:7], v[10:11]
	global_store_dwordx4 v[18:19], v[4:7], off offset:512 nt
	global_store_dwordx4 v[66:67], v[62:65], off nt
	global_store_dwordx4 v[66:67], v[58:61], off offset:64 nt
	v_pk_mul_f32 v[4:5], v[148:149], v[20:21] op_sel_hi:[1,0]
	v_pk_mul_f32 v[6:7], v[16:17], v[20:21] op_sel_hi:[1,0]
	v_pk_mul_f32 v[0:1], v[0:1], v[4:5]
	v_pk_mul_f32 v[2:3], v[2:3], v[6:7]
	global_store_dwordx4 v[66:67], v[54:57], off offset:512 nt
	global_store_dwordx4 v[50:51], v[46:49], off nt
	global_store_dwordx4 v[50:51], v[42:45], off offset:64 nt
	global_store_dwordx4 v[34:35], v[30:33], off nt
	global_store_dwordx4 v[34:35], v[26:29], off offset:64 nt
	global_store_dwordx4 v[18:19], v[0:3], off offset:576 nt
